# gathered items re-dealt between the eight waves before the item loop (each keeps at most ceil(total/8) of its own, short waves take slices of the others' surplus tails); every item still processed exa
# speedup vs baseline: 1.0349x; 1.0118x over previous
.LBB0_1389:
	s_waitcnt lgkmcnt(0)
	s_add_u32 s4, s16, s42
	s_addc_u32 s5, s17, s43
	s_add_u32 s48, s4, 0x3a00000
	s_addc_u32 s49, s5, 0
	s_waitcnt lgkmcnt(0)
	s_cmp_lt_i32 s44, 2
	s_cselect_b64 s[18:19], -1, 0
	s_add_u32 s50, s4, 0x4200000
	s_addc_u32 s51, s5, 0
	v_mov_b32_e32 v2, s52
	s_lshl_b32 s4, s64, 2
	s_add_i32 s4, s4, 0x11100
	v_mov_b32_e32 v3, s4
	ds_write_b32 v3, v2
	s_cmp_lt_i32 s52, 1
	s_cbranch_scc1 .Lsn_skip
	s_lshl_b32 s4, s52, 2
	s_add_i32 s4, s86, s4
	v_mov_b32_e32 v3, s4
	v_add_u32_e32 v4, -4, v3
	ds_read_b32 v2, v4
	s_waitcnt lgkmcnt(0)
	ds_write2_b32 v3, v2, v2 offset1:1
.Lsn_skip:
	v_mov_b32_e32 v2, 0
	v_mov_b32_e32 v3, 0
	v_mov_b32_e32 v4, 0
	v_mov_b32_e32 v5, 0
	v_mov_b32_e32 v6, 0
	v_mov_b32_e32 v7, 0
	v_mov_b32_e32 v8, 0
	v_mov_b32_e32 v9, 0
	v_mov_b32_e32 v10, 0
	v_mov_b32_e32 v11, 0
	v_mov_b32_e32 v12, 0
	v_mov_b32_e32 v13, 0
	v_mov_b32_e32 v14, 0
	v_mov_b32_e32 v15, 0
	v_mov_b32_e32 v16, 0
	v_mov_b32_e32 v17, 0
	v_mov_b32_e32 v18, 0
	v_mov_b32_e32 v19, 0
	v_mov_b32_e32 v20, 0
	v_mov_b32_e32 v21, 0
	v_mov_b32_e32 v22, 0
	v_mov_b32_e32 v23, 0
	v_mov_b32_e32 v24, 0
	v_mov_b32_e32 v25, 0
	v_mov_b32_e32 v26, 0
	v_mov_b32_e32 v27, 0
	v_mov_b32_e32 v28, 0
	v_mov_b32_e32 v29, 0
	v_mov_b32_e32 v30, 0
	v_mov_b32_e32 v31, 0
	v_mov_b32_e32 v32, 0
	v_mov_b32_e32 v33, 0
	v_mov_b32_e32 v1, 0
	v_mov_b32_e32 v162, 0xff800000
	v_mov_b32_e32 v236, 0x3fb8aa3b
	ds_read_b128 v[82:85], v224
	ds_read_b128 v[86:89], v224 offset:32
	ds_read_b128 v[90:93], v224 offset:64
	ds_read_b128 v[94:97], v224 offset:96
	s_lshl_b32 s4, s44, 13
	s_add_u32 s12, s48, s4
	s_addc_u32 s13, s49, 0
	s_waitcnt vmcnt(0)
	global_load_dwordx4 v[98:101], v194, s[12:13]
	global_load_dwordx4 v[102:105], v194, s[12:13] offset:1024
	global_load_dwordx4 v[106:109], v194, s[12:13] offset:2048
	global_load_dwordx4 v[110:113], v194, s[12:13] offset:3072
	global_load_dwordx4 v[114:117], v200, s[12:13]
	global_load_dwordx4 v[118:121], v202, s[12:13]
	global_load_dwordx4 v[122:125], v204, s[12:13]
	global_load_dwordx4 v[126:129], v206, s[12:13]
	s_waitcnt lgkmcnt(0)
	s_mov_b32 s26, s44
	s_lshl_b32 s4, s26, 13
	s_add_u32 s12, s50, s4
	s_addc_u32 s13, s51, 0
	global_load_dwordx4 v[130:133], v194, s[12:13]
	global_load_dwordx4 v[146:149], v200, s[12:13]
	global_load_dwordx4 v[134:137], v194, s[12:13] offset:1024
	global_load_dwordx4 v[150:153], v202, s[12:13]
	global_load_dwordx4 v[138:141], v194, s[12:13] offset:2048
	global_load_dwordx4 v[154:157], v204, s[12:13]
	global_load_dwordx4 v[142:145], v194, s[12:13] offset:3072
	global_load_dwordx4 v[158:161], v206, s[12:13]
	s_lshl_b32 s4, s26, 6
	v_subrev_u32_e32 v163, s4, v223
	v_sub_u32_e32 v163, v163, v226
	v_lshl_add_u32 v163, v163, 2, v225
	ds_read2_b32 v[66:67], v163 offset0:64 offset1:63
	ds_read2_b32 v[68:69], v163 offset0:62 offset1:61
	ds_read2_b32 v[70:71], v163 offset0:56 offset1:55
	ds_read2_b32 v[72:73], v163 offset0:54 offset1:53
	ds_read2_b32 v[74:75], v163 offset0:48 offset1:47
	ds_read2_b32 v[76:77], v163 offset0:46 offset1:45
	ds_read2_b32 v[78:79], v163 offset0:40 offset1:39
	ds_read2_b32 v[80:81], v163 offset0:38 offset1:37
	s_waitcnt vmcnt(8)
	v_mfma_f32_32x32x16_bf16 v[34:49], v[98:101], v[82:85], 0
	v_mfma_f32_32x32x16_bf16 v[50:65], v[114:117], v[82:85], 0
	v_mfma_f32_32x32x16_bf16 v[34:49], v[102:105], v[86:89], v[34:49]
	v_mfma_f32_32x32x16_bf16 v[50:65], v[118:121], v[86:89], v[50:65]
	v_mfma_f32_32x32x16_bf16 v[34:49], v[106:109], v[90:93], v[34:49]
	v_mfma_f32_32x32x16_bf16 v[50:65], v[122:125], v[90:93], v[50:65]
	v_mfma_f32_32x32x16_bf16 v[34:49], v[110:113], v[94:97], v[34:49]
	v_mfma_f32_32x32x16_bf16 v[50:65], v[126:129], v[94:97], v[50:65]
	s_cmp_gt_i32 s44, 0
	s_cbranch_scc1 .Lfe_a_has
	s_nop 9
	s_branch .Lfe_a_nok

.LBB0_1399:
	s_or_b64 exec, exec, s[12:13]
	s_add_u32 s4, s16, s42
	s_addc_u32 s5, s17, s43
	s_add_u32 s50, s4, 0x4200000
	s_addc_u32 s51, s5, 0
	s_waitcnt lgkmcnt(0)
	s_barrier
	s_cmp_gt_i32 s52, 0
	v_lshrrev_b32_e32 v2, 1, v210
	s_cselect_b64 s[20:21], -1, 0
	s_cmp_lt_i32 s52, 1
	v_add_u32_e32 v1, 0, v212
	v_add_u32_e32 v184, s87, v228
	v_and_b32_e32 v185, 16, v2
	v_add_u32_e32 v188, s91, v185
	v_mov_b32_e32 v141, 0xc1200000
	v_and_b32_e32 v2, 7, v229
	v_lshlrev_b32_e32 v2, 2, v2
	v_add_u32_e32 v2, 0x11100, v2
	ds_read_b32 v193, v2
	s_mov_b32 s75, 0
	s_waitcnt lgkmcnt(0)
	v_readlane_b32 s4, v193, 0
	v_readlane_b32 s5, v193, 1
	s_add_i32 s4, s4, s5
	v_readlane_b32 s5, v193, 2
	s_add_i32 s4, s4, s5
	v_readlane_b32 s5, v193, 3
	s_add_i32 s4, s4, s5
	v_readlane_b32 s5, v193, 4
	s_add_i32 s4, s4, s5
	v_readlane_b32 s5, v193, 5
	s_add_i32 s4, s4, s5
	v_readlane_b32 s5, v193, 6
	s_add_i32 s4, s4, s5
	v_readlane_b32 s5, v193, 7
	s_add_i32 s4, s4, s5
	s_add_i32 s74, s4, 7
	s_lshr_b32 s74, s74, 3
	v_readlane_b32 s5, v193, 0
	s_sub_i32 s5, s74, s5
	s_max_i32 s5, s5, 0
	s_cmp_gt_u32 s64, 0
	s_cselect_b32 s5, s5, 0
	s_add_i32 s75, s75, s5
	v_readlane_b32 s5, v193, 1
	s_sub_i32 s5, s74, s5
	s_max_i32 s5, s5, 0
	s_cmp_gt_u32 s64, 1
	s_cselect_b32 s5, s5, 0
	s_add_i32 s75, s75, s5
	v_readlane_b32 s5, v193, 2
	s_sub_i32 s5, s74, s5
	s_max_i32 s5, s5, 0
	s_cmp_gt_u32 s64, 2
	s_cselect_b32 s5, s5, 0
	s_add_i32 s75, s75, s5
	v_readlane_b32 s5, v193, 3
	s_sub_i32 s5, s74, s5
	s_max_i32 s5, s5, 0
	s_cmp_gt_u32 s64, 3
	s_cselect_b32 s5, s5, 0
	s_add_i32 s75, s75, s5
	v_readlane_b32 s5, v193, 4
	s_sub_i32 s5, s74, s5
	s_max_i32 s5, s5, 0
	s_cmp_gt_u32 s64, 4
	s_cselect_b32 s5, s5, 0
	s_add_i32 s75, s75, s5
	v_readlane_b32 s5, v193, 5
	s_sub_i32 s5, s74, s5
	s_max_i32 s5, s5, 0
	s_cmp_gt_u32 s64, 5
	s_cselect_b32 s5, s5, 0
	s_add_i32 s75, s75, s5
	v_readlane_b32 s5, v193, 6
	s_sub_i32 s5, s74, s5
	s_max_i32 s5, s5, 0
	s_cmp_gt_u32 s64, 6
	s_cselect_b32 s5, s5, 0
	s_add_i32 s75, s75, s5
	v_readlane_b32 s5, v193, 7
	s_sub_i32 s5, s74, s5
	s_max_i32 s5, s5, 0
	s_cmp_gt_u32 s64, 7
	s_cselect_b32 s5, s5, 0
	s_add_i32 s75, s75, s5
	s_sub_i32 s4, s74, s52
	s_max_i32 s4, s4, 0
	s_add_i32 s97, s75, s4
	s_mov_b32 s98, 0
	s_mov_b32 s100, -1
	s_min_u32 s32, s52, s74
	s_mov_b32 s101, s86
	v_mov_b32_e32 v134, v184
	s_cmp_eq_u32 s32, 0
	s_cbranch_scc0 .Lit_pre

.Lit_nextd:
	s_add_i32 s100, s100, 1
	s_cmp_gt_i32 s100, 7
	s_cbranch_scc1 .LBB0_1424
	s_cmp_ge_u32 s75, s97
	s_cbranch_scc1 .LBB0_1424
	v_readlane_b32 s4, v193, s100
	s_sub_i32 s4, s4, s74
	s_max_i32 s4, s4, 0
	s_mov_b32 s24, s98
	s_add_i32 s98, s98, s4
	s_max_u32 s22, s75, s24
	s_min_u32 s23, s97, s98
	s_cmp_gt_u32 s23, s22
	s_cbranch_scc0 .Lit_nextd
	s_sub_i32 s32, s23, s22
	s_sub_i32 s4, s22, s24
	s_add_i32 s4, s4, s74
	s_mul_i32 s5, s100, 0x220
	s_add_i32 s5, s5, 0x1b800
	s_lshl_b32 s22, s4, 2
	s_add_i32 s101, s5, s22
	s_mul_i32 s5, s100, 0x440
	s_add_i32 s5, s5, 0x1c900
	s_lshl_b32 s4, s4, 3
	s_add_i32 s5, s5, s4
	v_add_u32_e32 v134, s5, v228
	s_mov_b32 s75, s23
.Lit_pre:
	v_mov_b32_e32 v2, s101
	ds_read_b32 v2, v2
	s_mov_b32 s53, -1
	s_add_i32 s99, s101, 4
	s_waitcnt lgkmcnt(0)
	v_readfirstlane_b32 s26, v2
	s_lshl_b32 s4, s26, 13
	s_and_b32 s12, s4, 0x1fe000
	s_add_u32 s4, s48, s12
	s_addc_u32 s5, s49, 0
	s_add_u32 s12, s50, s12
	s_addc_u32 s13, s51, 0
	global_load_dwordx4 v[50:53], v194, s[4:5]
	global_load_dwordx4 v[54:57], v194, s[4:5] offset:1024
	global_load_dwordx4 v[58:61], v194, s[4:5] offset:2048
	global_load_dwordx4 v[62:65], v194, s[4:5] offset:3072
	global_load_dwordx4 v[66:69], v200, s[4:5]
	global_load_dwordx4 v[78:81], v202, s[4:5]
	global_load_dwordx4 v[90:93], v204, s[4:5]
	global_load_dwordx4 v[98:101], v206, s[4:5]
	global_load_dwordx4 v[74:77], v194, s[12:13]
	global_load_dwordx4 v[70:73], v194, s[12:13] offset:1024
	global_load_dwordx4 v[86:89], v194, s[12:13] offset:2048
	global_load_dwordx4 v[82:85], v194, s[12:13] offset:3072
	global_load_dwordx4 v[94:97], v200, s[12:13]
	global_load_dwordx4 v[102:105], v202, s[12:13]
	global_load_dwordx4 v[106:109], v204, s[12:13]
	global_load_dwordx4 v[110:113], v206, s[12:13]
	v_mov_b32_e32 v132, s99
	ds_read_b32 v133, v132
	ds_read_u8 v135, v134
	s_and_b32 s54, s26, 0xff
	s_add_i32 s99, s99, 4
	v_add_u32_e32 v134, 8, v134
	s_waitcnt lgkmcnt(0)
	v_readfirstlane_b32 s55, v133
	v_cmp_ne_u16_sdwa s[58:59], v135, s79 src0_sel:BYTE_0 src1_sel:DWORD
	s_and_b32 s4, s55, 0xff
	s_cmp_eq_u32 s4, s54
	s_cselect_b64 s[56:57], -1, 0
	v_cndmask_b32_e64 v135, 0, v135, s[58:59]
	v_and_b32_e32 v136, 63, v135
	v_lshl_or_b32 v130, v136, 2, v227
	v_mad_u32_u24 v137, v130, s66, v188
	ds_read_b128 v[114:117], v137
	ds_read_b128 v[118:121], v137 offset:32
	ds_read_b128 v[122:125], v137 offset:64
	ds_read_b128 v[126:129], v137 offset:96
	v_lshlrev_b32_e32 v138, 2, v130
	v_add_u32_e32 v138, 0x10d00, v138
	ds_read_b32 v139, v138
	s_waitcnt lgkmcnt(0)
	s_branch .Lit_commit

.Lit_nov:
	s_add_i32 s4, s53, 1
	s_cmp_ge_u32 s4, s32
	s_cbranch_scc1 .Lit_ret
